# attention: static s_setprio 1 for waves 4-7 during the tile loop
# speedup vs baseline: 1.0253x; 1.0253x over previous
; #define LAS __attribute__((address_space(3)))
; __device__ __forceinline__ int otid() { int t = threadIdx.x; asm volatile("" : "+v"(t)); return t; }
; #define WBAR() do { asm volatile("s_waitcnt vmcnt(0) lgkmcnt(0)" ::: "memory"); __builtin_amdgcn_s_barrier(); asm volatile("" ::: "memory"); } while (0)
; __device__ __forceinline__ void attn_unit(const unsigned char* __restrict__ Qb, const unsigned char* __restrict__ Kh, const unsigned char* __restrict__ VTh, f16* __restrict__ Ob, int seq, LAS char* lds) {
;     const int tid = otid(), wid = __builtin_amdgcn_readfirstlane(tid >> 6), lane = tid & 63, r32 = lane & 31, hi = lane >> 5;
;     LAS float* ws = (LAS float*)(lds + WS8) + wid * 64; LAS float* li_l = ws; LAS float* al_l = ws + 32;
;     f32x16 o[5] = {}; v8i qf[3]; f32x16 negm;
; #pragma unroll
;     for (int r = 0; r < 16; ++r) negm[r] = SH;
;     const unsigned char* Qw = Qb + (long)(wid * 32 + r32) * LDQ + hi * 32;
; #pragma unroll
;     for (int st = 0; st < 3; ++st) { const v4i x = *(const v4i*)(Qw + 64 * st), y = *(const v4i*)(Qw + 64 * st + 16); qf[st] = (v8i){x[0], x[1], x[2], x[3], y[0], y[1], y[2], y[3]}; }
;     const int sw = (r32 >> 2) & 3;
;     const int ka0 = r32 * 192 + (((2 * hi) ^ sw) << 4), ka1 = r32 * 192 + (((2 * hi + 1) ^ sw) << 4);
;     const int va0 = r32 * 64 + (((2 * hi) ^ sw) << 4), va1 = r32 * 64 + (((2 * hi + 1) ^ sw) << 4);
;     ...
;     f32x16 pA0, pA1, pB0, pB1; float dlA, dlB, alA, alB; v8i pa; const int NT = seq / 64;
;     const int NS = NT >> 1;
;     WBAR();
;     ISSUE(0);
;     WBAR();
;     if (1 < NS) ISSUE(1);
;     qkt(pA0, pA1, KSL(0), ka0, ka1, qf, negm); partialSM<true>(pA0, pA1, negm, dlA, alA);
.LBB0_586:
	v_lshrrev_b32_e32 v0, 2, v2
	v_bfe_u32 v2, v2, 2, 2
	v_lshlrev_b32_e32 v3, 1, v239
	v_bitop3_b32 v0, v3, v0, 3 bitop3:0x78
	v_bitop3_b32 v2, v3, v2, 1 bitop3:0x36
	v_lshlrev_b32_e32 v0, 4, v0
	v_lshlrev_b32_e32 v58, 4, v2
	v_mul_u32_u24_e32 v2, 0xc0, v238
	v_or_b32_e32 v244, v0, v2
	s_add_i32 m0, s15, 0
	v_or_b32_e32 v245, v58, v2
	global_load_lds_dwordx4 v4, s[0:1]
	v_add_u32_e32 v59, 0, v244
	v_add_u32_e32 v60, 0, v245
	ds_read_b128 v[2:5], v59 offset:49152
	ds_read_b128 v[6:9], v60 offset:49152
	v_readlane_b32 s68, v253, 62
	v_readlane_b32 s69, v253, 63
	v_readlane_b32 s70, v254, 0
	v_readlane_b32 s71, v254, 1
	v_readlane_b32 s72, v254, 2
	v_readlane_b32 s73, v254, 3
	v_readlane_b32 s74, v254, 4
	v_readlane_b32 s75, v254, 5
	v_readlane_b32 s76, v254, 6
	v_readlane_b32 s77, v254, 7
	v_readlane_b32 s78, v254, 8
	v_readlane_b32 s79, v254, 9
	v_readlane_b32 s80, v254, 10
	v_readlane_b32 s81, v254, 11
	v_readlane_b32 s82, v254, 12
	v_readlane_b32 s83, v254, 13
	s_mov_b32 s69, s68
	s_mov_b32 s70, s68
	s_mov_b32 s71, s68
	s_mov_b32 s72, s68
	s_mov_b32 s73, s68
	s_mov_b32 s74, s68
	s_mov_b32 s75, s68
	s_mov_b32 s76, s68
	s_mov_b32 s77, s68
	s_mov_b32 s78, s68
	s_mov_b32 s79, s68
	s_mov_b32 s80, s68
	s_mov_b32 s81, s68
	s_mov_b32 s82, s68
	s_mov_b32 s83, s68
	v_mov_b64_e32 v[18:19], s[68:69]
	v_mov_b64_e32 v[20:21], s[70:71]
	v_mov_b64_e32 v[22:23], s[72:73]
	v_mov_b64_e32 v[24:25], s[74:75]
	v_mov_b64_e32 v[26:27], s[76:77]
	v_mov_b64_e32 v[28:29], s[78:79]
	v_mov_b64_e32 v[30:31], s[80:81]
	v_mov_b64_e32 v[32:33], s[82:83]
	ds_read_b128 v[34:37], v59 offset:49216
	ds_read_b128 v[38:41], v60 offset:49216
	s_waitcnt vmcnt(0) lgkmcnt(0)
	v_mfma_scale_f32_32x32x64_f8f6f4 v[2:17], v[2:9], v[184:191], v[18:33], v234, v233 op_sel_hi:[0,0,0]
	ds_read_b128 v[46:49], v60 offset:55296
	ds_read_b128 v[42:45], v59 offset:55296
	ds_read_b128 v[50:53], v59 offset:49280
	ds_read_b128 v[54:57], v60 offset:49280
	s_mov_b32 s0, s68
	v_writelane_b32 v253, s0, 62
	s_lshl_b32 s28, s2, 13
	s_add_i32 s28, s28, s17
	v_writelane_b32 v254, s2, 0
	v_writelane_b32 v254, s3, 1
	v_writelane_b32 v254, s4, 2
	v_writelane_b32 v254, s5, 3
	v_writelane_b32 v254, s6, 4
	v_writelane_b32 v254, s7, 5
	v_writelane_b32 v254, s8, 6
	v_writelane_b32 v254, s9, 7
	v_writelane_b32 v254, s10, 8
	v_writelane_b32 v254, s11, 9
	s_waitcnt lgkmcnt(2)
	v_mfma_scale_f32_32x32x64_f8f6f4 v[18:33], v[42:49], v[184:191], v[18:33], v234, v233 op_sel_hi:[0,0,0]
	v_writelane_b32 v254, s12, 10
	v_writelane_b32 v254, s13, 11
	v_writelane_b32 v254, s14, 12
	v_writelane_b32 v254, s15, 13
	s_and_b32 s0, s14, 0x3fffffc0
	s_lshl_b32 s0, s0, 2
	s_add_i32 s20, s0, 0
	s_lshl_b32 s0, s2, 12
	s_lshl_b32 s35, s16, 13
	s_add_i32 s29, s28, s0
	s_add_i32 s35, s35, s19
	s_lshl_b32 s0, s16, 12
	s_lshl_b32 s26, s18, 13
	s_lshl_b32 s22, s2, 6
	s_add_i32 s2, s35, s0
	v_mfma_scale_f32_32x32x64_f8f6f4 v[2:17], v[34:41], v[176:183], v[2:17], v234, v233 op_sel_hi:[0,0,0]
	ds_read_b128 v[38:41], v60 offset:55360
	ds_read_b128 v[34:37], v59 offset:55360
	ds_read_b128 v[42:45], v59 offset:55424
	ds_read_b128 v[46:49], v60 offset:55424
	s_add_i32 s26, s26, s46
	s_lshl_b32 s0, s18, 12
	s_lshl_b32 s31, s33, 13
	s_add_i32 s20, s20, 0x18000
	s_add_i32 s27, s26, s0
	s_add_i32 s31, s31, s50
	s_lshl_b32 s0, s33, 12
	v_or_b32_e32 v246, 0x3800, v58
	v_or_b32_e32 v248, 0x3000, v58
	v_or_b32_e32 v249, 0x2800, v58
	v_or_b32_e32 v250, 0x2000, v58
	v_or_b32_e32 v251, 0x3800, v0
	v_or_b32_e32 v252, 0x3000, v0
	v_or_b32_e32 v231, 0x2800, v0
	s_waitcnt lgkmcnt(2)
	v_mfma_scale_f32_32x32x64_f8f6f4 v[18:33], v[34:41], v[176:183], v[18:33], v234, v233 op_sel_hi:[0,0,0]
	v_lshlrev_b32_e32 v34, 6, v238
	v_or_b32_e32 v240, v58, v34
	v_or_b32_e32 v241, v0, v34
	v_add_u32_e32 v247, 0, v34
	v_or_b32_e32 v218, 0x2000, v0
	v_mov_b32_e32 v0, v1
	v_writelane_b32 v253, s1, 63
	s_mov_b32 s21, 2
	s_lshr_b32 s47, s3, 6
	s_lshr_b32 s14, s3, 7
	s_mov_b32 s15, 0
	v_cmp_eq_u32_e64 s[12:13], 0, v239
	v_lshl_add_u32 v243, v238, 2, s20
	v_lshlrev_b32_e32 v242, 4, v239
	s_lshl_b32 s34, s16, 6
	v_mfma_scale_f32_32x32x64_f8f6f4 v[2:17], v[50:57], v[168:175], v[2:17], v234, v233 op_sel_hi:[0,0,0]
	s_lshl_b32 s3, s18, 6
	s_lshl_b32 s30, s33, 6
	s_add_i32 s49, s31, s0
	s_lshl_b32 s16, s42, 6
	s_add_i32 s18, s38, s51
	s_add_i32 s33, s39, s51
	s_mov_b32 s68, 0xfffe5000
	s_mov_b32 s69, 0xfffe6000
	s_mov_b32 s70, 0xfffe7000
	s_mov_b32 s71, 0xfffe8000
	s_mov_b32 s72, 0xfffe9000
	s_mov_b32 s73, 0xfffea000
	s_mov_b32 s74, 0xfffeb000
	s_mov_b32 s75, 0xfffec000
	s_mov_b32 s76, 0xfffed000
	s_waitcnt lgkmcnt(0)
; template <bool FIRST>
; __device__ __forceinline__ void partialSM(f32x16& p0, f32x16& p1, f32x16& negm, float& dl, float& alpha) {
;     float pmax = p0[0];
; #pragma unroll
;     for (int r = 1; r < 16; ++r) pmax = fmaxf(pmax, p0[r]);
; #pragma unroll
;     for (int r = 0; r < 16; ++r) pmax = fmaxf(pmax, p1[r]);
;     { auto rr = __builtin_amdgcn_permlane32_swap(__float_as_uint(pmax), __float_as_uint(pmax), false, false);
;       pmax = fmaxf(__uint_as_float(rr[0]), __uint_as_float(rr[1])); }
;     if (FIRST) {
;         dl = 0.f; alpha = 1.f; const float d0_ = pmax - SH;
; #pragma unroll
;         for (int r = 0; r < 16; ++r) { p0[r] -= d0_; p1[r] -= d0_; negm[r] -= d0_; }
;     } else {
;         const bool keep = __all(pmax <= SH + THRL);
;         dl = keep ? 0.f : fmaxf(pmax - SH, 0.f); alpha = __builtin_amdgcn_exp2f(-dl);
;     }
; #pragma unroll
;     for (int r = 0; r < 16; ++r) p0[r] = __builtin_amdgcn_exp2f(p0[r]);
	v_mfma_scale_f32_32x32x64_f8f6f4 v[18:33], v[42:49], v[168:175], v[18:33], v234, v233 op_sel_hi:[0,0,0]
	s_nop 2
	v_max_f32_e32 v35, v3, v3
	v_max_f32_e32 v36, v2, v2
	v_max_f32_e32 v35, v36, v35
	v_max3_f32 v35, v35, v4, v5
	v_max3_f32 v35, v35, v6, v7
	v_max3_f32 v35, v35, v8, v9
	v_max3_f32 v35, v35, v10, v11
	v_max3_f32 v35, v35, v12, v13
	v_max3_f32 v35, v35, v14, v15
	v_max3_f32 v35, v35, v16, v17
	s_mov_b32 s77, 0xfffee000
	s_mov_b32 s78, 0xfffef000
	s_mov_b32 s79, 0xffff0000
	s_mov_b32 s80, 0xffff1000
	s_mov_b32 s81, 0xffff2000
	s_nop 1
	v_max3_f32 v35, v35, v18, v19
	v_max3_f32 v35, v35, v20, v21
	v_max3_f32 v35, v35, v22, v23
	v_max3_f32 v35, v35, v24, v25
	v_max3_f32 v35, v35, v26, v27
	v_max3_f32 v35, v35, v28, v29
	v_max3_f32 v35, v35, v30, v31
	v_max3_f32 v35, v35, v32, v33
	v_mov_b32_e32 v36, v35
	s_nop 1
	v_permlane32_swap_b32_e32 v35, v36
	v_max_f32_e32 v36, v36, v36
	v_max_f32_e32 v35, v35, v35
	v_max_f32_e32 v35, v35, v36
	v_add_f32_e32 v35, -4.0, v35
	v_sub_f32_e32 v2, v2, v35
	v_exp_f32_e32 v228, v2
	v_sub_f32_e32 v2, v3, v35
	v_exp_f32_e32 v229, v2
	v_sub_f32_e32 v2, v4, v35
	v_exp_f32_e32 v220, v2
	v_sub_f32_e32 v2, v5, v35
	v_exp_f32_e32 v221, v2
	v_sub_f32_e32 v2, v6, v35
	v_exp_f32_e32 v226, v2
	v_sub_f32_e32 v2, v7, v35
	v_exp_f32_e32 v227, v2
	v_sub_f32_e32 v2, v8, v35
	v_exp_f32_e32 v224, v2
	v_sub_f32_e32 v2, v9, v35
	v_exp_f32_e32 v225, v2
	v_sub_f32_e32 v2, v10, v35
	v_exp_f32_e32 v222, v2
	v_sub_f32_e32 v2, v11, v35
	v_exp_f32_e32 v223, v2
	v_sub_f32_e32 v2, v12, v35
	v_exp_f32_e32 v162, v2
	v_sub_f32_e32 v2, v13, v35
	v_exp_f32_e32 v163, v2
	v_sub_f32_e32 v2, v14, v35
	v_exp_f32_e32 v166, v2
	v_sub_f32_e32 v2, v15, v35
	v_exp_f32_e32 v167, v2
	v_sub_f32_e32 v2, v16, v35
	v_exp_f32_e32 v164, v2
	v_sub_f32_e32 v2, v17, v35
	v_exp_f32_e32 v165, v2
	v_mov_b32_e32 v14, v1
	v_mov_b32_e32 v15, v1
	v_sub_f32_e32 v127, v33, v35
	v_sub_f32_e32 v126, v32, v35
	v_sub_f32_e32 v125, v31, v35
	v_sub_f32_e32 v124, v30, v35
	v_sub_f32_e32 v123, v29, v35
	v_sub_f32_e32 v122, v28, v35
	v_sub_f32_e32 v121, v27, v35
	v_sub_f32_e32 v120, v26, v35
	v_sub_f32_e32 v119, v25, v35
	v_sub_f32_e32 v118, v24, v35
	v_sub_f32_e32 v117, v23, v35
	v_sub_f32_e32 v116, v22, v35
	v_sub_f32_e32 v115, v21, v35
	v_sub_f32_e32 v114, v20, v35
	v_sub_f32_e32 v113, v19, v35
	v_sub_f32_e32 v112, v18, v35
	v_sub_f32_e32 v96, 4.0, v35
	v_mov_b32_e32 v2, v1
	v_mov_b32_e32 v3, v1
	v_mov_b32_e32 v4, v1
	v_mov_b32_e32 v5, v1
	v_mov_b32_e32 v6, v1
	v_mov_b32_e32 v7, v1
	v_mov_b32_e32 v8, v1
	v_mov_b32_e32 v9, v1
	v_mov_b32_e32 v10, v1
	v_mov_b32_e32 v11, v1
	v_mov_b32_e32 v12, v1
	v_mov_b32_e32 v13, v1
	v_mov_b64_e32 v[78:79], v[14:15]
	v_mov_b64_e32 v[62:63], v[14:15]
	v_mov_b64_e32 v[46:47], v[14:15]
	v_mov_b64_e32 v[30:31], v[14:15]
	v_mov_b64_e32 v[94:95], v[14:15]
	v_mov_b32_e32 v97, v96
	v_mov_b32_e32 v98, v96
	v_mov_b32_e32 v99, v96
	v_mov_b32_e32 v100, v96
	v_mov_b32_e32 v101, v96
	v_mov_b32_e32 v102, v96
	v_mov_b32_e32 v103, v96
	v_mov_b32_e32 v104, v96
	v_mov_b32_e32 v105, v96
	v_mov_b32_e32 v106, v96
	v_mov_b32_e32 v107, v96
	v_mov_b32_e32 v108, v96
	v_mov_b32_e32 v109, v96
	v_mov_b32_e32 v110, v96
	v_mov_b32_e32 v111, v96
	v_mov_b64_e32 v[76:77], v[12:13]
	v_mov_b64_e32 v[74:75], v[10:11]
	v_mov_b64_e32 v[72:73], v[8:9]
	v_mov_b64_e32 v[70:71], v[6:7]
	v_mov_b64_e32 v[68:69], v[4:5]
	v_mov_b64_e32 v[66:67], v[2:3]
	v_mov_b64_e32 v[64:65], v[0:1]
	v_mov_b64_e32 v[60:61], v[12:13]
	v_mov_b64_e32 v[58:59], v[10:11]
	v_mov_b64_e32 v[56:57], v[8:9]
	v_mov_b64_e32 v[54:55], v[6:7]
	v_mov_b64_e32 v[52:53], v[4:5]
	v_mov_b64_e32 v[50:51], v[2:3]
; __device__ __forceinline__ void attn_unit(const unsigned char* __restrict__ Qb, const unsigned char* __restrict__ Kh, const unsigned char* __restrict__ VTh, f16* __restrict__ Ob, int seq, LAS char* lds) {
;     ...
;     f32x16 o[5] = {}; v8i qf[3]; f32x16 negm;
	v_mov_b64_e32 v[48:49], v[0:1]
	v_mov_b64_e32 v[44:45], v[12:13]
	v_mov_b64_e32 v[42:43], v[10:11]
	v_mov_b64_e32 v[40:41], v[8:9]
	v_mov_b64_e32 v[38:39], v[6:7]
	v_mov_b64_e32 v[36:37], v[4:5]
	v_mov_b64_e32 v[34:35], v[2:3]
	v_mov_b64_e32 v[32:33], v[0:1]
	v_mov_b64_e32 v[28:29], v[12:13]
	v_mov_b64_e32 v[26:27], v[10:11]
	v_mov_b64_e32 v[24:25], v[8:9]
	v_mov_b64_e32 v[22:23], v[6:7]
	v_mov_b64_e32 v[20:21], v[4:5]
	v_mov_b64_e32 v[18:19], v[2:3]
	v_mov_b64_e32 v[16:17], v[0:1]
	v_mov_b64_e32 v[92:93], v[12:13]
	v_mov_b64_e32 v[90:91], v[10:11]
	v_mov_b64_e32 v[88:89], v[8:9]
	v_mov_b64_e32 v[86:87], v[6:7]
	v_mov_b64_e32 v[84:85], v[4:5]
	v_mov_b64_e32 v[82:83], v[2:3]
	v_mov_b64_e32 v[80:81], v[0:1]
	v_lshlrev_b32_e32 v2, 4, v216
	v_and_b32_e32 v2, 0x3f0, v2
	v_or_b32_e32 v3, 0xffffe000, v2
	v_add_u32_e32 v4, s17, v3
	s_mov_b32 s0, 0xaaaaaaab
	v_mul_hi_u32 v5, v4, s0
	v_lshrrev_b32_e32 v6, 7, v5
	s_movk_i32 s0, 0xc0
	v_mul_lo_u32 v7, v6, s0
	v_add_u32_e32 v6, s22, v6
	s_movk_i32 s0, 0x300
	v_lshrrev_b32_e32 v5, 5, v5
	v_sub_u32_e32 v4, v4, v7
	v_mul_lo_u32 v6, v6, s0
	v_and_b32_e32 v5, 48, v5
	v_bitop3_b32 v4, v5, v6, v4 bitop3:0xde
	v_or_b32_e32 v8, s28, v2
	v_cndmask_b32_e64 v12, v8, v4, s[56:57]
	v_add_u32_e32 v4, s19, v3
	s_mov_b32 s0, 0xaaaaaaab
	v_mul_hi_u32 v5, v4, s0
	v_lshrrev_b32_e32 v6, 7, v5
	s_movk_i32 s0, 0xc0
	v_mul_lo_u32 v7, v6, s0
	v_add_u32_e32 v6, s34, v6
	s_movk_i32 s0, 0x300
	v_lshrrev_b32_e32 v5, 5, v5
	v_sub_u32_e32 v4, v4, v7
	v_mul_lo_u32 v6, v6, s0
	v_and_b32_e32 v5, 48, v5
	v_bitop3_b32 v4, v5, v6, v4 bitop3:0xde
	v_or_b32_e32 v8, s35, v2
	v_cndmask_b32_e64 v13, v4, v8, s[4:5]
	v_add_u32_e32 v4, s46, v3
	s_mov_b32 s0, 0xaaaaaaab
	v_mul_hi_u32 v5, v4, s0
	v_lshrrev_b32_e32 v6, 7, v5
	s_movk_i32 s0, 0xc0
	v_mul_lo_u32 v7, v6, s0
	v_add_u32_e32 v6, s3, v6
	s_movk_i32 s0, 0x300
	v_lshrrev_b32_e32 v5, 5, v5
	v_sub_u32_e32 v4, v4, v7
	v_mul_lo_u32 v6, v6, s0
	v_and_b32_e32 v5, 48, v5
	v_bitop3_b32 v4, v5, v6, v4 bitop3:0xde
	v_or_b32_e32 v8, s26, v2
	v_cndmask_b32_e64 v14, v4, v8, s[6:7]
	v_add_u32_e32 v4, s50, v3
	s_mov_b32 s0, 0xaaaaaaab
	v_mul_hi_u32 v5, v4, s0
	v_lshrrev_b32_e32 v6, 7, v5
	s_movk_i32 s0, 0xc0
	v_mul_lo_u32 v7, v6, s0
	v_add_u32_e32 v6, s30, v6
	s_movk_i32 s0, 0x300
	v_lshrrev_b32_e32 v5, 5, v5
	v_sub_u32_e32 v4, v4, v7
	v_mul_lo_u32 v6, v6, s0
	v_and_b32_e32 v5, 48, v5
	v_bitop3_b32 v4, v5, v6, v4 bitop3:0xde
	v_or_b32_e32 v8, s31, v2
	v_cndmask_b32_e64 v15, v4, v8, s[8:9]
	v_add_u32_e32 v4, s51, v3
	s_mov_b32 s0, 0xaaaaaaab
	v_mul_hi_u32 v5, v4, s0
	v_lshrrev_b32_e32 v6, 7, v5
	s_movk_i32 s0, 0xc0
	v_mul_lo_u32 v7, v6, s0
	v_add_u32_e32 v6, s16, v6
	s_movk_i32 s0, 0x300
	v_lshrrev_b32_e32 v5, 5, v5
	v_sub_u32_e32 v4, v4, v7
	v_mul_lo_u32 v6, v6, s0
	v_and_b32_e32 v5, 48, v5
	v_bitop3_b32 v4, v5, v6, v4 bitop3:0xde
	v_or_b32_e32 v8, s18, v2
	v_cndmask_b32_e64 v9, v4, v8, s[10:11]
	v_mov_b32_e32 v5, 0x19000
	v_lshl_add_u32 v6, v216, 4, v5
	v_lshl_add_u32 v7, v216, 2, v5
	ds_write_b128 v6, v[12:15]
	ds_write_b32 v7, v9 offset:8192
	s_bitcmp1_b32 s15, 0
	s_cselect_b32 s1, 0x6000, 0
	v_add_u32_e32 v12, s1, v244
	v_add_u32_e32 v13, s1, v245
	v_add_u32_e32 v14, 0xf000, v12
	v_add_u32_e32 v15, 0xf000, v13
	ds_read_b128 v[202:205], v12 offset:61440
	ds_read_b128 v[206:209], v13 offset:61440
	ds_read_b128 v[194:197], v14 offset:6144
	ds_read_b128 v[198:201], v15 offset:6144
	s_mov_b32 s82, 0xffff3000
	s_mov_b32 s83, 0xffff4000
	v_readfirstlane_b32 s0, v216
	s_nop 3
	s_cmpk_lt_u32 s0, 0x100
	s_cbranch_scc1 .Lattn_prio_done
	s_setprio 1
.Lattn_prio_done:
	s_branch .LBB0_589

; #define SBAR() __builtin_amdgcn_sched_barrier(0)
; #define FIX(a, dlt, P0, P1) do { if (__any((dlt) > 0.f)) { if (hi == 0) al_l[r32] = (a); asm volatile("s_waitcnt lgkmcnt(0)" ::: "memory"); \
;     _Pragma("unroll") for (int d = 0; d < 5; ++d) _Pragma("unroll") for (int r = 0; r < 16; ++r) o[d][r] *= al_l[crow(r, hi)]; \
;     _Pragma("unroll") for (int r = 0; r < 16; ++r) { P0[r] *= (a); P1[r] -= (dlt); negm[r] -= (dlt); } } } while (0)
; __device__ __forceinline__ void attn_unit(const unsigned char* __restrict__ Qb, const unsigned char* __restrict__ Kh, const unsigned char* __restrict__ VTh, f16* __restrict__ Ob, int seq, LAS char* lds) {
;     ...
;     SBAR(); qkt(pB0, pB1, KSL(NT - 1), ka0, ka1, qf, negm);
;     finishSM(pA0, pA1, pa); SBAR();
;     pv_d0(o, VSL(NT - 2), va0, va1, pa); partialSM<false>(pB0, pB1, negm, dlB, alB);
;     FIX(alB, dlB, pB0, pB1);
.LBB0_618:
	s_setprio 0
	v_readlane_b32 s0, v253, 7
	v_exp_f32_e32 v13, v116
	v_exp_f32_e32 v14, v117
	v_add_u32_e32 v0, s0, v244
	v_add_u32_e32 v10, s0, v245
	ds_read_b128 v[2:5], v0
	ds_read_b128 v[6:9], v10
	v_exp_f32_e32 v116, v124
	s_waitcnt lgkmcnt(0)
	v_mfma_scale_f32_32x32x64_f8f6f4 v[128:143], v[2:9], v[184:191], v[96:111], v234, v233 op_sel_hi:[0,0,0]
	ds_read_b128 v[2:5], v0 offset:6144
	ds_read_b128 v[6:9], v10 offset:6144
	v_exp_f32_e32 v117, v125
	v_exp_f32_e32 v11, v114
	v_exp_f32_e32 v12, v115
	v_exp_f32_e32 v15, v118
	v_exp_f32_e32 v114, v122
	v_exp_f32_e32 v115, v123
	v_exp_f32_e32 v118, v126
	s_waitcnt lgkmcnt(0)
	v_mfma_scale_f32_32x32x64_f8f6f4 v[96:111], v[2:9], v[184:191], v[96:111], v234, v233 op_sel_hi:[0,0,0]
	ds_read_b128 v[2:5], v0 offset:64
	ds_read_b128 v[6:9], v10 offset:64
	s_waitcnt lgkmcnt(0)
	v_mfma_scale_f32_32x32x64_f8f6f4 v[128:143], v[2:9], v[176:183], v[128:143], v234, v233 op_sel_hi:[0,0,0]
	ds_read_b128 v[2:5], v0 offset:6208
	ds_read_b128 v[6:9], v10 offset:6208
	ds_read_b128 v[144:147], v0 offset:6272
	ds_read_b128 v[148:151], v10 offset:6272
	ds_read_b128 v[152:155], v0 offset:128
	ds_read_b128 v[156:159], v10 offset:128
	v_exp_f32_e32 v10, v113
	v_exp_f32_e32 v113, v120
	v_exp_f32_e32 v0, v112
	v_exp_f32_e32 v112, v119
	v_exp_f32_e32 v119, v127
	s_waitcnt lgkmcnt(0)
	v_mfma_scale_f32_32x32x64_f8f6f4 v[96:111], v[2:9], v[176:183], v[96:111], v234, v233 op_sel_hi:[0,0,0]
	v_exp_f32_e32 v5, v121
	v_mov_b32_e32 v8, v1
	v_mov_b32_e32 v2, v1
	v_mov_b32_e32 v6, v1
	v_mov_b32_e32 v3, v1
	v_mov_b32_e32 v7, v1
	v_mov_b32_e32 v4, v1
	v_cvt_pk_fp8_f32 v8, v113, v5
	v_mov_b32_e32 v5, v1
	v_mov_b32_e32 v9, v1
	v_cvt_pk_fp8_f32 v2, v228, v229
	v_cvt_pk_fp8_f32 v6, v0, v10
	v_cvt_pk_fp8_f32 v3, v226, v227
	v_cvt_pk_fp8_f32 v7, v13, v14
	v_cvt_pk_fp8_f32 v4, v222, v223
	v_mfma_scale_f32_32x32x64_f8f6f4 v[96:111], v[144:151], v[168:175], v[96:111], v234, v233 op_sel_hi:[0,0,0]
	v_cvt_pk_fp8_f32 v5, v166, v167
	v_cvt_pk_fp8_f32 v9, v116, v117
	v_cvt_pk_fp8_f32 v2, v220, v221 op_sel:[0,0,1]
	v_cvt_pk_fp8_f32 v6, v11, v12 op_sel:[0,0,1]
	v_cvt_pk_fp8_f32 v3, v224, v225 op_sel:[0,0,1]
	v_cvt_pk_fp8_f32 v7, v15, v112 op_sel:[0,0,1]
	v_cvt_pk_fp8_f32 v4, v162, v163 op_sel:[0,0,1]
	v_cvt_pk_fp8_f32 v8, v114, v115 op_sel:[0,0,1]
	v_cvt_pk_fp8_f32 v5, v164, v165 op_sel:[0,0,1]
	v_cvt_pk_fp8_f32 v9, v118, v119 op_sel:[0,0,1]
	v_mfma_scale_f32_32x32x64_f8f6f4 v[128:143], v[152:159], v[168:175], v[128:143], v234, v233 op_sel_hi:[0,0,0]
	s_add_i32 s0, s47, -2
	s_lshr_b32 s0, s0, 1
	s_mul_hi_u32 s1, s0, 0x55555556
	s_mul_i32 s1, s1, 3
	s_sub_i32 s0, s0, s1
	s_lshl_b32 s0, s0, 14
	s_add_i32 s0, s0, 0
	v_add_u32_e32 v0, s0, v241
	v_add_u32_e32 v10, s0, v240
	ds_read_b128 v[112:115], v0
	ds_read_b128 v[116:119], v10
	v_mov_b32_e32 v161, v160
	v_mov_b32_e32 v162, v160
	v_mov_b32_e32 v163, v160
	s_waitcnt lgkmcnt(0)
	v_mfma_scale_f32_32x32x64_f8f6f4 v[64:79], v[2:9], v[112:119], v[64:79], v234, v234 op_sel_hi:[0,0,0]
	ds_read_b128 v[112:115], v0 offset:2048
	ds_read_b128 v[116:119], v10 offset:2048
	v_mov_b32_e32 v164, v160
	v_mov_b32_e32 v165, v160
	v_mov_b32_e32 v166, v160
	v_mov_b32_e32 v167, v160
	v_exp_f32_e32 v14, v128
	v_exp_f32_e32 v15, v129
	v_exp_f32_e32 v12, v134
	v_exp_f32_e32 v13, v135
	v_exp_f32_e32 v11, v137
	s_waitcnt lgkmcnt(0)
	v_mfma_scale_f32_32x32x64_f8f6f4 v[48:63], v[2:9], v[112:119], v[48:63], v234, v234 op_sel_hi:[0,0,0]
	ds_read_b128 v[112:115], v0 offset:4096
	ds_read_b128 v[116:119], v10 offset:4096
	s_waitcnt lgkmcnt(0)
	v_mfma_scale_f32_32x32x64_f8f6f4 v[32:47], v[2:9], v[112:119], v[32:47], v234, v234 op_sel_hi:[0,0,0]
	ds_read_b128 v[112:115], v0 offset:6144
	ds_read_b128 v[116:119], v10 offset:6144
	v_max_f32_e32 v0, v129, v129
	v_exp_f32_e32 v10, v136
	s_waitcnt lgkmcnt(0)
	v_mfma_scale_f32_32x32x64_f8f6f4 v[16:31], v[2:9], v[112:119], v[16:31], v234, v234 op_sel_hi:[0,0,0]
	v_exp_f32_e32 v112, v132
	v_exp_f32_e32 v113, v133
	v_mfma_scale_f32_32x32x64_f8f6f4 v[80:95], v[2:9], v[160:167], v[80:95], v234, v234 op_sel_hi:[0,0,0]
	v_max_f32_e32 v2, v128, v128
	v_max_f32_e32 v0, v2, v0
	v_max3_f32 v0, v0, v130, v131
	v_max3_f32 v0, v0, v132, v133
	v_max3_f32 v0, v0, v134, v135
	v_max3_f32 v0, v0, v136, v137
	v_max3_f32 v0, v0, v138, v139
	v_max3_f32 v0, v0, v140, v141
	v_max3_f32 v0, v0, v142, v143
	v_max3_f32 v0, v0, v96, v97
	v_max3_f32 v0, v0, v98, v99
	v_max3_f32 v0, v0, v100, v101
	v_max3_f32 v0, v0, v102, v103
	v_max3_f32 v0, v0, v104, v105
	v_max3_f32 v0, v0, v106, v107
	v_max3_f32 v0, v0, v108, v109
	v_max3_f32 v0, v0, v110, v111
	v_mov_b32_e32 v2, v0
	s_nop 1
	v_permlane32_swap_b32_e32 v0, v2
	v_max_f32_e32 v2, v2, v2
	v_max_f32_e32 v0, v0, v0
	v_max_f32_e32 v0, v0, v2
	v_cmp_ge_f32_e32 vcc, s67, v0
	v_add_f32_e32 v0, -4.0, v0
	s_cmp_lg_u64 vcc, exec
	v_exp_f32_e32 v8, v130
	v_exp_f32_e32 v9, v131
	v_exp_f32_e32 v2, v138
	v_exp_f32_e32 v3, v139
	v_exp_f32_e32 v6, v140
	v_exp_f32_e32 v7, v141
	v_exp_f32_e32 v4, v142
	v_exp_f32_e32 v5, v143
	v_max_f32_e32 v0, 0, v0
	s_cselect_b64 vcc, -1, 0
	v_cndmask_b32_e32 v0, 0, v0, vcc
	v_cmp_lt_f32_e32 vcc, 0, v0
	s_cbranch_vccz .LBB0_621
	v_exp_f32_e64 v114, -v0
	s_mov_b64 s[0:1], exec
	v_readlane_b32 s58, v255, 13
	v_readlane_b32 s56, v255, 15
	v_readlane_b32 s30, v255, 19
	v_readlane_b32 s34, v255, 21
	s_and_b64 s[2:3], s[0:1], s[12:13]
	v_readlane_b32 s64, v254, 14
	s_movk_i32 s49, 0x7f
	s_movk_i32 s63, 0x4000
	s_mov_b32 s62, 0x2aaaaaab
	s_movk_i32 s60, 0xff80
	s_movk_i32 s61, 0xa00
	v_readlane_b32 s59, v255, 14
	v_readlane_b32 s57, v255, 16
	v_readlane_b32 s31, v255, 20
	v_readlane_b32 s35, v255, 22
	v_readlane_b32 s6, v255, 23
	v_mov_b32_e32 v231, v219
	v_readlane_b32 s65, v254, 15
	v_readlane_b32 s7, v255, 24
	s_mov_b64 exec, s[2:3]
	s_cbranch_execz .LBB0_500
	ds_write_b32 v243, v114 offset:128
	s_branch .LBB0_500
